# ATT2F unit prologue: dropped the vmcnt(0) drains before the first K/V LDS-DMA and before the tile loop (counted waits already cover the Q loads)
# speedup vs baseline: 1.0025x; 1.0025x over previous
; #define ATT_WAIT_BAR(n) asm volatile("s_waitcnt vmcnt(" #n ")\n\ts_barrier" ::: "memory")
; template <bool DIFF, bool FIXED, bool F32SRC> ...
;     ...
;     const int lane = tid & 63, w = __builtin_amdgcn_readfirstlane(tid >> 6), q32 = lane & 31, hi = lane >> 5;
;     const int sub = DIFF ? (w & 1) : 0, qg = DIFF ? (w >> 1) : w;
;     const bool wact = (32 * qg < u.nq);
;     const int qloc = u.qloc0 + 32 * qg + q32, cq = (u.qloc0 + 32 * qg) >> 6;
;     const bool qvalid = (32 * qg + q32) < u.nq;
;     const int qrow = qvalid ? (u.qrow0 + 32 * qg + q32) : u.qrow0;
;     bf16x8 qf[4];
; #pragma unroll
;     for (int ks = 0; ks < 4; ++ks) qf[ks] = *(const bf16x8*)(Q + (size_t)qrow * PITCH + u.h * HW + sub * 64 + ks * 16 + hi * 8);
;     float mrun = mref0, lrun = 0.f; f32x16 o[NDB];
; #pragma unroll
;     for (int db = 0; db < NDB; ++db) o[db] = f32x16{};
;     unsigned kgo[NCH], vgo[NCH];
; #pragma unroll
;     for (int i = 0; i < NCH; ++i) {
;         const int piece = w * NCH + i;
;         const int krow = DIFF ? (piece * 4 + (lane >> 4)) : (piece * 8 + (lane >> 3));
;         const int kcp = DIFF ? (lane & 15) : (lane & 7);
;         const int kch = kcp ^ (DIFF ? (krow & 15) : ((krow >> 1) & 7));
;         kgo[i] = (unsigned)(krow * PITCH + kch * 8);
;         const int p = piece * 64 + lane, st = p >> 5, key = 8 * (st / NDB) + ((p & 31) >> 2), dch = (st % NDB) * 4 + (p & 3);
;         vgo[i] = (unsigned)(key * PITCH + dch * 8);
;     }
;     ...
;     const int vlane = (4 * hi + ((lane & 15) >> 2)) * 64 + ((lane >> 4) & 1) * 32 + (lane & 3) * 8;
;     const int kswz = DIFF ? (q32 & 15) : ((q32 >> 1) & 7);
;     int koff[4];
; #pragma unroll
;     for (int ks = 0; ks < 4; ++ks) koff[ks] = q32 * RB + (((sub * 8 + 2 * ks + hi) ^ kswz) << 4);
;     int j = u.jhi, buf = 0;
;     if (!F32SRC) {
;     asm volatile("s_waitcnt vmcnt(0)" ::: "memory");
;     ATT_DMA(j, 0);
;     if (j - 1 >= u.jlo) { ATT_DMA(j - 1, 1); if (NCH == 2) ATT_WAIT_BAR(4); else ATT_WAIT_BAR(2); }
;     else ATT_WAIT_BAR(0);
.LBB0_404:
	s_and_b64 vcc, exec, s[0:1]
	s_cbranch_vccz .LBB0_424
	v_mov_b32_e32 v67, v196
	v_mov_b32_e32 v3, s28
	v_readfirstlane_b32 s0, v67
	s_ashr_i32 s61, s0, 7
	v_and_b32_e32 v66, 31, v67
	s_lshl_b32 s16, s61, 5
	s_ashr_i32 s17, s0, 6
	v_or_b32_e32 v0, s16, v66
	v_or_b32_e32 v2, s28, v66
	s_movk_i32 s0, 0x80
	v_add_u32_e32 v2, s16, v2
	v_cmp_gt_i32_e64 s[10:11], s0, v0
	v_readlane_b32 s0, v254, 21
	v_readlane_b32 s1, v254, 22
	v_cndmask_b32_e64 v2, v3, v2, s[10:11]
	v_ashrrev_i32_e32 v3, 31, v2
	v_lshlrev_b64 v[2:3], 11, v[2:3]
	s_and_b32 s62, s17, 1
	v_lshl_add_u64 v[2:3], s[0:1], 0, v[2:3]
	s_lshl_b32 s90, s60, 1
	v_bfe_u32 v68, v67, 5, 1
	v_lshl_add_u64 v[130:131], v[2:3], 0, s[90:91]
	s_lshl_b32 s0, s62, 7
	s_mov_b32 s1, s91
	v_lshl_add_u64 v[2:3], v[130:131], 0, s[0:1]
	v_lshlrev_b32_e32 v0, 4, v68
	v_lshl_add_u64 v[2:3], v[2:3], 0, v[0:1]
	v_lshlrev_b32_e32 v0, 3, v67
	global_load_dwordx4 v[98:101], v[2:3], off
	global_load_dwordx4 v[102:105], v[2:3], off offset:32
	global_load_dwordx4 v[106:109], v[2:3], off offset:64
	global_load_dwordx4 v[110:113], v[2:3], off offset:96
	v_lshlrev_b32_e32 v3, 8, v67
	v_and_b32_e32 v0, 24, v0
	s_movk_i32 s1, 0x1c00
	v_bfe_u32 v2, v67, 4, 2
	v_and_or_b32 v3, v3, s1, v0
	s_lshl_b32 s1, s17, 3
	v_or_b32_e32 v4, s1, v2
	v_bitop3_b32 v5, s1, v67, v2 bitop3:0x36
	v_and_b32_e32 v195, 63, v67
	v_lshlrev_b32_e32 v4, 10, v4
	v_lshlrev_b32_e32 v5, 3, v5
	s_movk_i32 s12, 0x78
	v_and_or_b32 v136, v5, s12, v4
	v_lshl_or_b32 v4, s17, 7, v195
	v_ashrrev_i32_e32 v4, 5, v4
	v_ashrrev_i32_e32 v5, 31, v4
	v_lshrrev_b32_e32 v5, 30, v5
	s_lshl_b32 s0, s17, 1
	v_add_u32_e32 v5, v4, v5
	v_and_b32_e32 v6, 0x7fffffc, v5
	v_lshlrev_b32_e32 v5, 11, v5
	s_movk_i32 s13, 0xe000
	s_or_b32 s0, s0, 1
	v_sub_u32_e32 v4, v4, v6
	v_and_or_b32 v5, v5, s13, v3
	s_lshl_b32 s1, s0, 2
	v_lshl_add_u32 v138, v4, 5, v5
	v_or_b32_e32 v4, s1, v2
	v_bitop3_b32 v2, s1, v67, v2 bitop3:0x36
	v_lshlrev_b32_e32 v4, 10, v4
	v_lshlrev_b32_e32 v2, 3, v2
	v_and_or_b32 v140, v2, s12, v4
	v_lshl_or_b32 v2, s0, 6, v195
	v_ashrrev_i32_e32 v2, 5, v2
	v_ashrrev_i32_e32 v4, 31, v2
	v_lshrrev_b32_e32 v4, 30, v4
	s_lshl_b32 s0, s50, 6
	v_add_u32_e32 v4, v2, v4
	s_add_i32 s0, s0, s51
	v_and_b32_e32 v5, 0x7fffffc, v4
	v_lshlrev_b32_e32 v4, 11, v4
	s_ashr_i32 s1, s0, 31
	v_and_or_b32 v3, v4, s13, v3
	s_lshl_b64 s[12:13], s[0:1], 11
	s_add_u32 s1, s74, s12
	s_addc_u32 s19, s75, s13
	s_add_u32 s18, s1, s90
	s_addc_u32 s19, s19, 0
	v_readlane_b32 s36, v252, 55
	v_readlane_b32 s37, v252, 56
	s_add_u32 s1, s36, s12
	s_addc_u32 s13, s37, s13
	s_add_u32 s12, s1, s90
	s_addc_u32 s13, s13, 0
	s_lshl_b32 s1, s17, 11
	v_sub_u32_e32 v2, v2, v5
	v_mov_b32_e32 v137, v1
	s_add_i32 s51, s1, 0
	v_lshl_add_u32 v142, v2, 5, v3
	v_lshl_add_u64 v[2:3], v[136:137], 1, s[18:19]
	s_mov_b32 m0, s51
	v_mov_b32_e32 v139, v1
	global_load_lds_dwordx4 v[2:3], off
	v_lshl_add_u64 v[2:3], v[138:139], 1, s[12:13]
	s_add_i32 m0, s51, 0x4000
	v_mov_b32_e32 v141, v1
	global_load_lds_dwordx4 v[2:3], off
	v_lshl_add_u64 v[2:3], v[140:141], 1, s[18:19]
	s_add_i32 m0, s51, 0x400
	v_mov_b32_e32 v143, v1
	global_load_lds_dwordx4 v[2:3], off
	v_lshl_add_u64 v[2:3], v[142:143], 1, s[12:13]
	s_add_i32 m0, s51, 0x4400
	s_cmp_lt_i32 s25, s24
	global_load_lds_dwordx4 v[2:3], off
	s_mov_b64 s[12:13], -1
	s_cbranch_scc1 .LBB0_407
	s_sub_i32 s0, s0, 64
	s_ashr_i32 s1, s0, 31
	s_lshl_b64 s[0:1], s[0:1], 11
	s_add_u32 s12, s74, s0
	s_addc_u32 s13, s75, s1
	s_add_u32 s12, s12, s90
	s_addc_u32 s13, s13, 0
	v_readlane_b32 s18, v252, 55
	v_readlane_b32 s19, v252, 56
	s_add_u32 s0, s18, s0
	s_addc_u32 s1, s19, s1
	s_add_u32 s0, s0, s90
	s_addc_u32 s1, s1, 0
	v_lshl_add_u64 v[2:3], v[136:137], 1, s[12:13]
	s_add_i32 m0, s51, 0x8000
	s_nop 0
	global_load_lds_dwordx4 v[2:3], off
	v_lshl_add_u64 v[2:3], v[138:139], 1, s[0:1]
	s_add_i32 m0, s51, 0xc000
	s_nop 0
	global_load_lds_dwordx4 v[2:3], off
	v_lshl_add_u64 v[2:3], v[140:141], 1, s[12:13]
	s_add_i32 m0, s51, 0x8400
	s_mov_b64 s[12:13], 0
	global_load_lds_dwordx4 v[2:3], off
	v_lshl_add_u64 v[2:3], v[142:143], 1, s[0:1]
	s_add_i32 m0, s51, 0xc400
	s_nop 0
	global_load_lds_dwordx4 v[2:3], off
	s_waitcnt vmcnt(4)
	s_barrier

; template <bool DIFF, bool FIXED, bool F32SRC> ...
;     ...
;     float mrun = mref0, lrun = 0.f; f32x16 o[NDB];
; #pragma unroll
;     for (int db = 0; db < NDB; ++db) o[db] = f32x16{};
;     unsigned kgo[NCH], vgo[NCH];
; #pragma unroll
;     for (int i = 0; i < NCH; ++i) {
;         const int piece = w * NCH + i;
;         const int krow = DIFF ? (piece * 4 + (lane >> 4)) : (piece * 8 + (lane >> 3));
;         const int kcp = DIFF ? (lane & 15) : (lane & 7);
;         const int kch = kcp ^ (DIFF ? (krow & 15) : ((krow >> 1) & 7));
;         kgo[i] = (unsigned)(krow * PITCH + kch * 8);
;         const int p = piece * 64 + lane, st = p >> 5, key = 8 * (st / NDB) + ((p & 31) >> 2), dch = (st % NDB) * 4 + (p & 3);
;         vgo[i] = (unsigned)(key * PITCH + dch * 8);
;     }
;     ...
;     const int vlane = (4 * hi + ((lane & 15) >> 2)) * 64 + ((lane >> 4) & 1) * 32 + (lane & 3) * 8;
;     const int kswz = DIFF ? (q32 & 15) : ((q32 >> 1) & 7);
;     int koff[4];
; #pragma unroll
;     for (int ks = 0; ks < 4; ++ks) koff[ks] = q32 * RB + (((sub * 8 + 2 * ks + hi) ^ kswz) << 4);
;     int j = u.jhi, buf = 0;
.LBB0_409:
	s_cmp_lt_i32 s61, 4
	v_mov_b32_e32 v17, 0
	s_cselect_b64 s[0:1], -1, 0
	v_lshlrev_b32_e32 v194, 2, v68
	s_cmp_lt_i32 s50, s24
	v_mov_b32_e32 v16, v17
	v_mov_b32_e32 v15, v17
	v_mov_b32_e32 v14, v17
	v_mov_b32_e32 v13, v17
	v_mov_b32_e32 v12, v17
	v_mov_b32_e32 v11, v17
	v_mov_b32_e32 v10, v17
	v_mov_b32_e32 v9, v17
	v_mov_b32_e32 v8, v17
	v_mov_b32_e32 v7, v17
	v_mov_b32_e32 v6, v17
	v_mov_b32_e32 v5, v17
	v_mov_b32_e32 v4, v17
	v_mov_b32_e32 v3, v17
	v_mov_b32_e32 v2, v17
	v_mov_b32_e32 v33, v17
	v_mov_b32_e32 v32, v17
	v_mov_b32_e32 v31, v17
	v_mov_b32_e32 v30, v17
	v_mov_b32_e32 v29, v17
	v_mov_b32_e32 v28, v17
	v_mov_b32_e32 v27, v17
	v_mov_b32_e32 v26, v17
	v_mov_b32_e32 v25, v17
	v_mov_b32_e32 v24, v17
	v_mov_b32_e32 v23, v17
	v_mov_b32_e32 v22, v17
	v_mov_b32_e32 v21, v17
	v_mov_b32_e32 v20, v17
	v_mov_b32_e32 v19, v17
	v_mov_b32_e32 v18, v17
	v_mov_b32_e32 v49, v17
	v_mov_b32_e32 v48, v17
	v_mov_b32_e32 v47, v17
	v_mov_b32_e32 v46, v17
	v_mov_b32_e32 v45, v17
	v_mov_b32_e32 v44, v17
	v_mov_b32_e32 v43, v17
	v_mov_b32_e32 v42, v17
	v_mov_b32_e32 v41, v17
	v_mov_b32_e32 v40, v17
	v_mov_b32_e32 v39, v17
	v_mov_b32_e32 v38, v17
	v_mov_b32_e32 v37, v17
	v_mov_b32_e32 v36, v17
	v_mov_b32_e32 v35, v17
	v_mov_b32_e32 v34, v17
	v_mov_b32_e32 v65, v17
	v_mov_b32_e32 v64, v17
	v_mov_b32_e32 v63, v17
	v_mov_b32_e32 v62, v17
	v_mov_b32_e32 v61, v17
	v_mov_b32_e32 v60, v17
	v_mov_b32_e32 v59, v17
	v_mov_b32_e32 v58, v17
	v_mov_b32_e32 v57, v17
	v_mov_b32_e32 v56, v17
	v_mov_b32_e32 v55, v17
	v_mov_b32_e32 v54, v17
	v_mov_b32_e32 v53, v17
	v_mov_b32_e32 v52, v17
	v_mov_b32_e32 v51, v17
	v_mov_b32_e32 v50, v17
	v_mov_b32_e32 v219, v17
	s_cbranch_scc1 .LBB0_462
	s_add_u32 s50, s74, s90
	s_addc_u32 s60, s75, 0
	v_readlane_b32 s12, v252, 55
	v_readlane_b32 s13, v252, 56
	s_add_u32 s63, s12, s90
	v_lshrrev_b32_e32 v2, 2, v67
	s_addc_u32 s64, s13, 0
	s_add_i32 s12, s16, s30
	v_and_or_b32 v2, v2, 3, v194
	v_lshlrev_b32_e32 v3, 1, v67
	v_and_b32_e32 v4, 15, v67
	s_lshl_b32 s13, s62, 3
	v_and_b32_e32 v3, 32, v3
	v_or_b32_e32 v5, s13, v68
	v_bitop3_b32 v6, s13, v4, v68 bitop3:0x36
	v_lshlrev_b32_e32 v2, 6, v2
	s_ashr_i32 s30, s12, 6
	s_mov_b32 s12, 2.0
	v_or3_b32 v225, v2, v3, v0
	v_mov_b32_e32 v0, v135
	s_mov_b32 s13, 0x40400000
	v_pk_mul_f32 v[162:163], v[0:1], s[12:13] op_sel_hi:[0,1]
	s_mov_b32 s12, 0x41000000
	s_mov_b32 s13, 0x41100000
	v_pk_mul_f32 v[164:165], v[0:1], s[12:13] op_sel_hi:[0,1]
	s_mov_b32 s12, 0x41200000
	s_mov_b32 s13, 0x41300000
	v_pk_mul_f32 v[166:167], v[0:1], s[12:13] op_sel_hi:[0,1]
	s_mov_b32 s12, 0x41800000
	s_mov_b32 s13, 0x41880000
	v_pk_mul_f32 v[168:169], v[0:1], s[12:13] op_sel_hi:[0,1]
	s_mov_b32 s12, 0x41900000
	s_mov_b32 s13, 0x41980000
	v_pk_mul_f32 v[170:171], v[0:1], s[12:13] op_sel_hi:[0,1]
	s_mov_b32 s12, 0x41c00000
	s_mov_b32 s13, 0x41c80000
	v_pk_mul_f32 v[172:173], v[0:1], s[12:13] op_sel_hi:[0,1]
	s_mov_b32 s12, 0x41d00000
	s_mov_b32 s13, 0x41d80000
	v_pk_mul_f32 v[174:175], v[0:1], s[12:13] op_sel_hi:[0,1]
	s_mov_b32 s12, 0x42680000
	s_mov_b32 s13, 0x426c0000
	v_pk_mul_f32 v[178:179], v[0:1], s[12:13] op_sel_hi:[0,1]
	s_mov_b32 s12, 0x42600000
	s_mov_b32 s13, 0x42640000
	v_pk_mul_f32 v[180:181], v[0:1], s[12:13] op_sel_hi:[0,1]
	s_mov_b32 s12, 0x42480000
	s_mov_b32 s13, 0x424c0000
	v_pk_mul_f32 v[182:183], v[0:1], s[12:13] op_sel_hi:[0,1]
	s_mov_b32 s12, 0x42400000
	s_mov_b32 s13, 0x42440000
	v_pk_mul_f32 v[184:185], v[0:1], s[12:13] op_sel_hi:[0,1]
	s_mov_b32 s12, 0x42280000
	s_mov_b32 s13, 0x422c0000
	v_pk_mul_f32 v[186:187], v[0:1], s[12:13] op_sel_hi:[0,1]
	s_mov_b32 s12, 0x42200000
	s_mov_b32 s13, 0x42240000
	v_pk_mul_f32 v[188:189], v[0:1], s[12:13] op_sel_hi:[0,1]
	s_mov_b32 s12, 0x42080000
	s_mov_b32 s13, 0x420c0000
	v_pk_mul_f32 v[190:191], v[0:1], s[12:13] op_sel_hi:[0,1]
	s_mov_b32 s12, 0x42000000
	s_mov_b32 s13, 0x42040000
	v_lshlrev_b32_e32 v221, 4, v6
	v_bitop3_b32 v6, v5, v4, 2 bitop3:0x36
	v_pk_mul_f32 v[192:193], v[0:1], s[12:13] op_sel_hi:[0,1]
	s_sub_i32 s12, s16, 64
	v_lshlrev_b32_e32 v222, 4, v6
	v_bitop3_b32 v6, v5, v4, 4 bitop3:0x36
	v_bitop3_b32 v4, v5, v4, 6 bitop3:0x36
	v_xor_b32_e32 v144, 0x80000000, v135
	v_mov_b32_e32 v219, 0
	v_add_u32_e32 v0, s12, v66
	v_lshlrev_b32_e32 v220, 8, v66
	v_lshlrev_b32_e32 v223, 4, v6
	v_lshlrev_b32_e32 v224, 4, v4
	s_sub_i32 s29, s30, s29
	v_mul_f32_e32 v134, 0, v135
	v_mov_b32_e32 v176, v144
	v_mov_b32_e32 v177, v144
	v_sub_u32_e32 v226, v0, v194
	s_add_i32 s25, s25, -1
	s_sub_i32 s12, s28, 64
	s_mov_b32 s28, 0
	v_mov_b32_e32 v50, 0
	v_mov_b32_e32 v51, v219
	v_mov_b32_e32 v52, v219
	v_mov_b32_e32 v53, v219
	v_mov_b32_e32 v54, v219
	v_mov_b32_e32 v55, v219
	v_mov_b32_e32 v56, v219
	v_mov_b32_e32 v57, v219
	v_mov_b32_e32 v58, v219
	v_mov_b32_e32 v59, v219
	v_mov_b32_e32 v60, v219
	v_mov_b32_e32 v61, v219
	v_mov_b32_e32 v62, v219
	v_mov_b32_e32 v63, v219
	v_mov_b32_e32 v64, v219
	v_mov_b32_e32 v65, v219
	v_mov_b32_e32 v34, 0
	v_mov_b32_e32 v35, v219
	v_mov_b32_e32 v36, v219
	v_mov_b32_e32 v37, v219
	v_mov_b32_e32 v38, v219
	v_mov_b32_e32 v39, v219
	v_mov_b32_e32 v40, v219
	v_mov_b32_e32 v41, v219
	v_mov_b32_e32 v42, v219
	v_mov_b32_e32 v43, v219
	v_mov_b32_e32 v44, v219
	v_mov_b32_e32 v45, v219
	v_mov_b32_e32 v46, v219
	v_mov_b32_e32 v47, v219
	v_mov_b32_e32 v48, v219
	v_mov_b32_e32 v49, v219
	v_mov_b32_e32 v18, 0
	v_mov_b32_e32 v19, v219
	v_mov_b32_e32 v20, v219
	v_mov_b32_e32 v21, v219
	v_mov_b32_e32 v22, v219
	v_mov_b32_e32 v23, v219
	v_mov_b32_e32 v24, v219
	v_mov_b32_e32 v25, v219
	v_mov_b32_e32 v26, v219
	v_mov_b32_e32 v27, v219
	v_mov_b32_e32 v28, v219
	v_mov_b32_e32 v29, v219
	v_mov_b32_e32 v30, v219
	v_mov_b32_e32 v31, v219
	v_mov_b32_e32 v32, v219
	v_mov_b32_e32 v33, v219
	v_mov_b32_e32 v2, 0
	v_mov_b32_e32 v3, v219
	v_mov_b32_e32 v4, v219
	v_mov_b32_e32 v5, v219
	v_mov_b32_e32 v6, v219
	v_mov_b32_e32 v7, v219
	v_mov_b32_e32 v8, v219
	v_mov_b32_e32 v9, v219
	v_mov_b32_e32 v10, v219
	v_mov_b32_e32 v11, v219
	v_mov_b32_e32 v12, v219
	v_mov_b32_e32 v13, v219
	v_mov_b32_e32 v14, v219
	v_mov_b32_e32 v15, v219
	v_mov_b32_e32 v16, v219
	v_mov_b32_e32 v17, v219
	s_branch .LBB0_412
